# plain-store GEMM units (QKV in-projection, FFN down, out-projection): dedicated straight-line bf16 store epilogue for full tiles instead of the generic per-chunk mode dispatch
# baseline (speedup 1.0000x reference)
; __device__ __forceinline__ unsigned cvtpk(float lo, float hi) { f32x2 v = {lo, hi}; bf16x2_t b = __builtin_convertvector(v, bf16x2_t); return __builtin_bit_cast(unsigned, b); }
; __device__ __forceinline__ float bflo(unsigned u) { return __uint_as_float(u << 16); }
; __device__ __forceinline__ float bfhi(unsigned u) { return __uint_as_float(u & 0xffff0000u); }
; __device__ __forceinline__ float sigmoidf_(float x) { return fast_rcp(1.f + __expf(-x)); }
;     __device__ __forceinline__ void operator()(const f32x4 (&acc)[2][2][4][2], const Unit& u, int wr, int wc, int fr, int fq) const {
;     ...
;                 for (int bj = 0; bj < 2; ++bj) { const int cl = cl0 + bj * HALF; const int col0 = u.pn * BM + cl; f32x4 v0 = acc[ai][bj][m][0], v1 = acc[ai][bj][m][1];
;                     if (mode == 2) {
;                         float r[4];
; #pragma unroll
;                         for (int e = 0; e < 4; ++e) r[e] = v0[e] * sigmoidf_(v0[e]) * v1[e];
;                         u32x2 w; w.x = cvtpk(r[0], r[1]); w.y = cvtpk(r[2], r[3]);
;                         *(u32x2*)(rowp + (col0 >> 1)) = w;
;                     } else {
;                         if (mode == 1 || mode == 5) {
; #pragma unroll
;                             for (int e = 0; e < 4; ++e) { v0[e] = sigmoidf_(v0[e]); v1[e] = sigmoidf_(v1[e]); } }
;                         if (mode == 6) {
;                             const u32x4 gq = *(const u32x4*)(sG + rl * 256 + cl);
;                             v0[0] *= bflo(gq.x); v0[1] *= bfhi(gq.x); v0[2] *= bflo(gq.y); v0[3] *= bfhi(gq.y); v1[0] *= bflo(gq.z); v1[1] *= bfhi(gq.z); v1[2] *= bflo(gq.w); v1[3] *= bfhi(gq.w);
;                             if (u.br > 0) { const u32x4 mo = *(const u32x4*)(sM + rl * 256 + cl);
;                                 v0[0] += bflo(mo.x); v0[1] += bfhi(mo.x); v0[2] += bflo(mo.y); v0[3] += bfhi(mo.y); v1[0] += bflo(mo.z); v1[1] += bfhi(mo.z); v1[2] += bflo(mo.w); v1[3] += bfhi(mo.w); } }
;                         u32x4 w; w.x = cvtpk(v0[0], v0[1]); w.y = cvtpk(v0[2], v0[3]); w.z = cvtpk(v1[0], v1[1]); w.w = cvtpk(v1[2], v1[3]);
;                         if (mode == 5) *(u32x4*)(sG + rl * 256 + cl) = w;
;                         else if (mode == 6 && u.br < 2) *(u32x4*)(sM + rl * 256 + cl) = w;
;                         else if (col0 < ncols) *(u32x4*)(rowp + col0) = w; } } }
.LBB0_423:
	s_cmp_eq_u32 s71, 6
	s_cbranch_scc1 .Lepi6
	s_cmp_eq_u32 s71, 5
	s_cbranch_scc1 .Lepi5
	s_cmp_lg_u32 s71, 0
	s_cbranch_scc1 .Lepi0_no
	s_lshl_b32 s74, s69, 8
	s_add_i32 s74, s74, 0x100
	s_cmp_le_i32 s74, s52
	s_cbranch_scc1 .Lepi0

; __device__ __forceinline__ unsigned cvtpk(float lo, float hi) { f32x2 v = {lo, hi}; bf16x2_t b = __builtin_convertvector(v, bf16x2_t); return __builtin_bit_cast(unsigned, b); }
; __device__ __forceinline__ float bflo(unsigned u) { return __uint_as_float(u << 16); }
;     __device__ __forceinline__ void operator()(const f32x4 (&acc)[2][2][4][2], const Unit& u, int wr, int wc, int fr, int fq) const {
;     ...
;         for (int ai = 0; ai < 2; ++ai)
; #pragma unroll
;             for (int m = 0; m < 4; ++m) { const int rl = rl0 + ai * HALF + m * 16; const size_t row = (size_t)(u.pm * BM + rl); bf16_t* rowp = O + row * ldc;
; #pragma unroll
;                 for (int bj = 0; bj < 2; ++bj) { const int cl = cl0 + bj * HALF; const int col0 = u.pn * BM + cl; f32x4 v0 = acc[ai][bj][m][0], v1 = acc[ai][bj][m][1];
;                     if (mode == 2) {
;                         float r[4];
; #pragma unroll
;                         for (int e = 0; e < 4; ++e) r[e] = v0[e] * sigmoidf_(v0[e]) * v1[e];
;                         u32x2 w; w.x = cvtpk(r[0], r[1]); w.y = cvtpk(r[2], r[3]);
;                         *(u32x2*)(rowp + (col0 >> 1)) = w;
;                     } else {
;                         if (mode == 1 || mode == 5) {
; #pragma unroll
;                             for (int e = 0; e < 4; ++e) { v0[e] = sigmoidf_(v0[e]); v1[e] = sigmoidf_(v1[e]); } }
;                         if (mode == 6) {
;                             const u32x4 gq = *(const u32x4*)(sG + rl * 256 + cl);
;                             v0[0] *= bflo(gq.x); v0[1] *= bfhi(gq.x); v0[2] *= bflo(gq.y); v0[3] *= bfhi(gq.y); v1[0] *= bflo(gq.z); v1[1] *= bfhi(gq.z); v1[2] *= bflo(gq.w); v1[3] *= bfhi(gq.w);
;                             if (u.br > 0) { const u32x4 mo = *(const u32x4*)(sM + rl * 256 + cl);
;                                 v0[0] += bflo(mo.x); v0[1] += bfhi(mo.x); v0[2] += bflo(mo.y); v0[3] += bfhi(mo.y); v1[0] += bflo(mo.z); v1[1] += bfhi(mo.z); v1[2] += bflo(mo.w); v1[3] += bfhi(mo.w); } }
;                         u32x4 w; w.x = cvtpk(v0[0], v0[1]); w.y = cvtpk(v0[2], v0[3]); w.z = cvtpk(v1[0], v1[1]); w.w = cvtpk(v1[2], v1[3]);
;                         if (mode == 5) *(u32x4*)(sG + rl * 256 + cl) = w;
;                         else if (mode == 6 && u.br < 2) *(u32x4*)(sM + rl * 256 + cl) = w;
;                         else if (col0 < ncols) *(u32x4*)(rowp + col0) = w; } } }
.Lepi0:
	s_lshl_b32 s74, s0, 1
	v_mul_lo_u32 v228, v184, s74
	v_lshl_add_u32 v228, v150, 1, v228
	s_lshl_b32 s75, s68, 8
	s_mul_hi_u32 s77, s75, s74
	s_mul_i32 s76, s75, s74
	s_add_u32 s78, s24, s76
	s_addc_u32 s79, s25, s77
	s_lshl_b32 s75, s69, 9
	s_add_u32 s78, s78, s75
	s_addc_u32 s79, s79, 0
	s_lshl_b32 s81, s74, 4
	s_lshl_b32 s80, s74, 7
	s_mov_b32 s90, s78
	s_mov_b32 s91, s79
	v_cvt_pk_bf16_f32 v246, v132, v133
	v_cvt_pk_bf16_f32 v247, v134, v135
	v_cvt_pk_bf16_f32 v248, v128, v129
	v_cvt_pk_bf16_f32 v249, v130, v131
	global_store_dwordx4 v228, v[246:249], s[90:91]
	v_cvt_pk_bf16_f32 v210, v100, v101
	v_cvt_pk_bf16_f32 v211, v102, v103
	v_cvt_pk_bf16_f32 v212, v96, v97
	v_cvt_pk_bf16_f32 v213, v98, v99
	global_store_dwordx4 v228, v[210:213], s[90:91] offset:256
	s_add_u32 s90, s90, s81
	s_addc_u32 s91, s91, 0
	v_cvt_pk_bf16_f32 v246, v124, v125
	v_cvt_pk_bf16_f32 v247, v126, v127
	v_cvt_pk_bf16_f32 v248, v120, v121
	v_cvt_pk_bf16_f32 v249, v122, v123
	global_store_dwordx4 v228, v[246:249], s[90:91]
	v_cvt_pk_bf16_f32 v210, v92, v93
	v_cvt_pk_bf16_f32 v211, v94, v95
	v_cvt_pk_bf16_f32 v212, v88, v89
	v_cvt_pk_bf16_f32 v213, v90, v91
	global_store_dwordx4 v228, v[210:213], s[90:91] offset:256
	s_add_u32 s90, s90, s81
	s_addc_u32 s91, s91, 0
	v_cvt_pk_bf16_f32 v246, v116, v117
	v_cvt_pk_bf16_f32 v247, v118, v119
	v_cvt_pk_bf16_f32 v248, v112, v113
	v_cvt_pk_bf16_f32 v249, v114, v115
	global_store_dwordx4 v228, v[246:249], s[90:91]
	v_cvt_pk_bf16_f32 v210, v84, v85
	v_cvt_pk_bf16_f32 v211, v86, v87
	v_cvt_pk_bf16_f32 v212, v80, v81
	v_cvt_pk_bf16_f32 v213, v82, v83
	global_store_dwordx4 v228, v[210:213], s[90:91] offset:256
	s_add_u32 s90, s90, s81
	s_addc_u32 s91, s91, 0
	v_cvt_pk_bf16_f32 v246, v108, v109
	v_cvt_pk_bf16_f32 v247, v110, v111
	v_cvt_pk_bf16_f32 v248, v104, v105
	v_cvt_pk_bf16_f32 v249, v106, v107
	global_store_dwordx4 v228, v[246:249], s[90:91]
	v_cvt_pk_bf16_f32 v210, v76, v77
	v_cvt_pk_bf16_f32 v211, v78, v79
	v_cvt_pk_bf16_f32 v212, v72, v73
	v_cvt_pk_bf16_f32 v213, v74, v75
	global_store_dwordx4 v228, v[210:213], s[90:91] offset:256
	s_add_u32 s90, s78, s80
	s_addc_u32 s91, s79, 0
	v_cvt_pk_bf16_f32 v246, v68, v69
	v_cvt_pk_bf16_f32 v247, v70, v71
	v_cvt_pk_bf16_f32 v248, v64, v65
	v_cvt_pk_bf16_f32 v249, v66, v67
	global_store_dwordx4 v228, v[246:249], s[90:91]
	v_cvt_pk_bf16_f32 v210, v36, v37
	v_cvt_pk_bf16_f32 v211, v38, v39
	v_cvt_pk_bf16_f32 v212, v32, v33
	v_cvt_pk_bf16_f32 v213, v34, v35
	global_store_dwordx4 v228, v[210:213], s[90:91] offset:256
	s_add_u32 s90, s90, s81
	s_addc_u32 s91, s91, 0
	v_cvt_pk_bf16_f32 v246, v60, v61
	v_cvt_pk_bf16_f32 v247, v62, v63
	v_cvt_pk_bf16_f32 v248, v56, v57
	v_cvt_pk_bf16_f32 v249, v58, v59
	global_store_dwordx4 v228, v[246:249], s[90:91]
	v_cvt_pk_bf16_f32 v210, v28, v29
	v_cvt_pk_bf16_f32 v211, v30, v31
	v_cvt_pk_bf16_f32 v212, v24, v25
	v_cvt_pk_bf16_f32 v213, v26, v27
	global_store_dwordx4 v228, v[210:213], s[90:91] offset:256
	s_add_u32 s90, s90, s81
	s_addc_u32 s91, s91, 0
	v_cvt_pk_bf16_f32 v246, v52, v53
	v_cvt_pk_bf16_f32 v247, v54, v55
	v_cvt_pk_bf16_f32 v248, v48, v49
	v_cvt_pk_bf16_f32 v249, v50, v51
	global_store_dwordx4 v228, v[246:249], s[90:91]
	v_cvt_pk_bf16_f32 v210, v20, v21
	v_cvt_pk_bf16_f32 v211, v22, v23
	v_cvt_pk_bf16_f32 v212, v16, v17
	v_cvt_pk_bf16_f32 v213, v18, v19
	global_store_dwordx4 v228, v[210:213], s[90:91] offset:256
	s_add_u32 s90, s90, s81
	s_addc_u32 s91, s91, 0
	v_cvt_pk_bf16_f32 v246, v44, v45
	v_cvt_pk_bf16_f32 v247, v46, v47
	v_cvt_pk_bf16_f32 v248, v40, v41
	v_cvt_pk_bf16_f32 v249, v42, v43
	global_store_dwordx4 v228, v[246:249], s[90:91]
	v_cvt_pk_bf16_f32 v210, v12, v13
	v_cvt_pk_bf16_f32 v211, v14, v15
	v_cvt_pk_bf16_f32 v212, v8, v9
	v_cvt_pk_bf16_f32 v213, v10, v11
	global_store_dwordx4 v228, v[210:213], s[90:91] offset:256
	s_branch .LBB0_422
